# attention: also exp of sub-tile B issued between the PV MFMAs of sub-tile A (fast path)
# speedup vs baseline: 1.0094x; 1.0023x over previous
; #define LAS __attribute__((address_space(3)))
; __device__ __forceinline__ void attn_pv(const bf16x8 (&vf)[8], const bf16x8 (&pb)[4], f32x16& o0, f32x16& o1) {
; #pragma unroll
;     for (int s = 0; s < 4; ++s) {
;         o0 = __builtin_amdgcn_mfma_f32_32x32x16_bf16(vf[2 * s], pb[s], o0, 0, 0, 0);
;         o1 = __builtin_amdgcn_mfma_f32_32x32x16_bf16(vf[2 * s + 1], pb[s], o1, 0, 0, 0);
;     }
; }
; __device__ __forceinline__ void attn_phase(LAS unsigned char* lds, const bf16_t* __restrict__ Q, const bf16_t* __restrict__ KN, const bf16_t* __restrict__ KR,
;                                            const bf16_t* __restrict__ VT, bf16_t* AO, int vcu, int G, int tid, int lane, int wave) {
;     ...
;                     attn_softmax(a0, a1, pa, o0, o1, m_run, l_run);
;                     attn_ldv(vf, vA);
;                     __builtin_amdgcn_sched_barrier(0);
;                     PREFETCH_NEXT();
;                     attn_ldv(vf2, vA + 128);
;                     __builtin_amdgcn_sched_barrier(0);
;                     attn_pv(vf, pa, o0, o1);
;                     attn_softmax(b0, b1, pb2, o0, o1, m_run, l_run);
;                     __builtin_amdgcn_sched_barrier(0);
;                     attn_pv(vf2, pb2, o0, o1);
;                 } else if (2 * t <= qc) {
;                     bf16x8 kf[12], vf[8], pa[4]; f32x16 a0, a1;
;                     PREFETCH_NEXT();
;                     attn_ldk(kf, kA);
;                     __builtin_amdgcn_sched_barrier(0);
;                     attn_qk(a0, a1, kf, qf);
;                     __builtin_amdgcn_sched_barrier(0);
;                     attn_ldv(vf, vA);
;                     __builtin_amdgcn_sched_barrier(0);
;                     attn_softmax(a0, a1, pa, o0, o1, m_run, l_run);
;                     __builtin_amdgcn_sched_barrier(0);
;                     attn_pv(vf, pa, o0, o1);
;                 } else { PREFETCH_NEXT(); }
;                 if (more) { LAS unsigned char* nb = lds + ((t + 1) & 1) * BUF;
;                     *(LAS u32x4*)(nb + kdst) = gk0; *(LAS u32x4*)(nb + kdst + 64 * KP * 2) = gk1; *(LAS u32x4*)(nb + rdst) = gr; *(LAS u32x4*)(nb + vdst) = gv0; *(LAS u32x4*)(nb + vdst + 128) = gv1; }
.Lat_fast_A2:
	v_add_f32_e32 v227, v227, v1
	v_cvt_pk_bf16_f32 v34, v34, v35
	v_cvt_pk_bf16_f32 v35, v36, v37
	v_cvt_pk_bf16_f32 v36, v38, v39
	v_cvt_pk_bf16_f32 v37, v40, v41
	v_cvt_pk_bf16_f32 v42, v42, v43
	v_cvt_pk_bf16_f32 v43, v44, v45
	v_cvt_pk_bf16_f32 v44, v46, v47
	v_cvt_pk_bf16_f32 v45, v48, v49
	v_cvt_pk_bf16_f32 v50, v50, v51
	v_cvt_pk_bf16_f32 v51, v52, v53
	v_cvt_pk_bf16_f32 v52, v54, v55
	v_cvt_pk_bf16_f32 v53, v56, v57
	v_cvt_pk_bf16_f32 v58, v58, v59
	v_cvt_pk_bf16_f32 v59, v60, v61
	v_cvt_pk_bf16_f32 v60, v62, v63
	v_cvt_pk_bf16_f32 v61, v64, v65
	s_cmp_lg_u32 s6, 0
	s_cbranch_scc1 .Lat_plain_B2
	s_cmp_lg_u32 s7, 0
	s_cbranch_scc1 .Lat_plain_B2
	s_waitcnt lgkmcnt(5)
	v_mfma_f32_32x32x16_bf16 v[2:17], v[170:173], v[34:37], v[2:17]
	ds_read_b128 v[170:173], v225 offset:26720
	v_exp_f32_e32 v66, v66
	v_exp_f32_e32 v82, v82
	v_exp_f32_e32 v67, v67
	v_exp_f32_e32 v83, v83
	s_waitcnt lgkmcnt(5)
	v_mfma_f32_32x32x16_bf16 v[18:33], v[174:177], v[34:37], v[18:33]
	ds_read_b128 v[174:177], v225 offset:35424
	s_waitcnt vmcnt(0)
	v_add_u32_e32 v226, s38, v219
	ds_write_b128 v226, v[228:231]
	v_exp_f32_e32 v68, v68
	v_exp_f32_e32 v84, v84
	v_exp_f32_e32 v69, v69
	v_exp_f32_e32 v85, v85
	s_waitcnt lgkmcnt(6)
	v_mfma_f32_32x32x16_bf16 v[2:17], v[178:181], v[42:45], v[2:17]
	ds_read_b128 v[178:181], v225 offset:26752
	ds_write_b128 v226, v[232:235] offset:13312
	v_exp_f32_e32 v70, v70
	v_exp_f32_e32 v86, v86
	v_exp_f32_e32 v71, v71
	v_exp_f32_e32 v87, v87
	s_waitcnt lgkmcnt(7)
	v_mfma_f32_32x32x16_bf16 v[18:33], v[182:185], v[42:45], v[18:33]
	ds_read_b128 v[182:185], v225 offset:35456
	v_add_u32_e32 v226, s38, v220
	ds_write_b128 v226, v[236:239]
	v_exp_f32_e32 v72, v72
	v_exp_f32_e32 v88, v88
	v_exp_f32_e32 v73, v73
	v_exp_f32_e32 v89, v89
	s_waitcnt lgkmcnt(8)
	v_mfma_f32_32x32x16_bf16 v[2:17], v[186:189], v[50:53], v[2:17]
	ds_read_b128 v[186:189], v225 offset:26784
	v_add_u32_e32 v226, s38, v221
	ds_write_b128 v226, v[240:243] offset:26624
	v_exp_f32_e32 v74, v74
	v_exp_f32_e32 v90, v90
	v_exp_f32_e32 v75, v75
	v_exp_f32_e32 v91, v91
	s_waitcnt lgkmcnt(9)
	v_mfma_f32_32x32x16_bf16 v[18:33], v[190:193], v[50:53], v[18:33]
	ds_read_b128 v[190:193], v225 offset:35488
	ds_write_b128 v226, v[244:247] offset:26752
	v_exp_f32_e32 v76, v76
	v_exp_f32_e32 v92, v92
	v_exp_f32_e32 v77, v77
	v_exp_f32_e32 v93, v93
	s_waitcnt lgkmcnt(10)
	v_mfma_f32_32x32x16_bf16 v[2:17], v[170:173], v[58:61], v[2:17]
	ds_read_b128 v[170:173], v225 offset:26816
	v_exp_f32_e32 v78, v78
	v_exp_f32_e32 v94, v94
	v_exp_f32_e32 v79, v79
	v_exp_f32_e32 v95, v95
	s_waitcnt lgkmcnt(10)
	v_mfma_f32_32x32x16_bf16 v[18:33], v[174:177], v[58:61], v[18:33]
	ds_read_b128 v[174:177], v225 offset:35520
	v_exp_f32_e32 v80, v80
	v_exp_f32_e32 v96, v96
	v_exp_f32_e32 v81, v81
	v_exp_f32_e32 v97, v97
	s_mov_b32 s41, 0
	s_branch .Lat_sum_B2
.Lat_plain_B2:
	s_waitcnt lgkmcnt(5)
	v_mfma_f32_32x32x16_bf16 v[2:17], v[170:173], v[34:37], v[2:17]
	ds_read_b128 v[170:173], v225 offset:26720
	s_waitcnt lgkmcnt(5)
	v_mfma_f32_32x32x16_bf16 v[18:33], v[174:177], v[34:37], v[18:33]
	ds_read_b128 v[174:177], v225 offset:35424
	s_waitcnt vmcnt(0)
	v_add_u32_e32 v226, s38, v219
	ds_write_b128 v226, v[228:231]
	s_waitcnt lgkmcnt(6)
	v_mfma_f32_32x32x16_bf16 v[2:17], v[178:181], v[42:45], v[2:17]
	ds_read_b128 v[178:181], v225 offset:26752
	ds_write_b128 v226, v[232:235] offset:13312
	s_waitcnt lgkmcnt(7)
	v_mfma_f32_32x32x16_bf16 v[18:33], v[182:185], v[42:45], v[18:33]
	ds_read_b128 v[182:185], v225 offset:35456
	v_add_u32_e32 v226, s38, v220
	ds_write_b128 v226, v[236:239]
	s_waitcnt lgkmcnt(8)
	v_mfma_f32_32x32x16_bf16 v[2:17], v[186:189], v[50:53], v[2:17]
	ds_read_b128 v[186:189], v225 offset:26784
	v_add_u32_e32 v226, s38, v221
	ds_write_b128 v226, v[240:243] offset:26624
	s_waitcnt lgkmcnt(9)
	v_mfma_f32_32x32x16_bf16 v[18:33], v[190:193], v[50:53], v[18:33]
	ds_read_b128 v[190:193], v225 offset:35488
	ds_write_b128 v226, v[244:247] offset:26752
	s_waitcnt lgkmcnt(10)
	v_mfma_f32_32x32x16_bf16 v[2:17], v[170:173], v[58:61], v[2:17]
	ds_read_b128 v[170:173], v225 offset:26816
	s_waitcnt lgkmcnt(10)
	v_mfma_f32_32x32x16_bf16 v[18:33], v[174:177], v[58:61], v[18:33]
	ds_read_b128 v[174:177], v225 offset:35520
	s_cmp_lg_u32 s6, 0
	s_cbranch_scc1 .Lat_fix_B

; __device__ __forceinline__ void attn_softmax(f32x16& p0, f32x16& p1, bf16x8 (&pb)[4], f32x16& o0, f32x16& o1, float& m_run, float& l_run) {
;     ...
;     f32x16 sm = p0 + p1;
;     f32x2v s2 = (f32x2v){sm[0], sm[1]} + (f32x2v){sm[2], sm[3]};
; #pragma unroll
;     for (int r = 4; r < 16; r += 2) s2 += (f32x2v){sm[r], sm[r + 1]};
;     l_run = l_run * alpha + (s2[0] + s2[1]);
.Lat_sum_B2:
	v_pk_add_f32 v[250:251], v[66:67], v[68:69]
	v_pk_add_f32 v[252:253], v[82:83], v[84:85]
	v_pk_add_f32 v[250:251], v[250:251], v[70:71]
	v_pk_add_f32 v[252:253], v[252:253], v[86:87]
	v_pk_add_f32 v[250:251], v[250:251], v[72:73]
	v_pk_add_f32 v[252:253], v[252:253], v[88:89]
	v_pk_add_f32 v[250:251], v[250:251], v[74:75]
	v_pk_add_f32 v[252:253], v[252:253], v[90:91]
	v_pk_add_f32 v[250:251], v[250:251], v[76:77]
	v_pk_add_f32 v[252:253], v[252:253], v[92:93]
	v_pk_add_f32 v[250:251], v[250:251], v[78:79]
	v_pk_add_f32 v[252:253], v[252:253], v[94:95]
	v_pk_add_f32 v[250:251], v[250:251], v[80:81]
	v_pk_add_f32 v[252:253], v[252:253], v[96:97]
	v_pk_add_f32 v[250:251], v[250:251], v[252:253]
	v_add_f32_e32 v1, v250, v251
	v_cmp_lt_f32_e32 vcc, s26, v1
	s_cbranch_vccnz .Lat_rare_B2
